# MLA hand-written tile loop + static prio for waves 4-7; swa K/V staging loads de-serialized; sgu W-tile loads de-serialized
# speedup vs baseline: 1.0251x; 1.0076x over previous
; #define LAS __attribute__((address_space(3)))
;     ...
;   for (int it = bid_; it < 512; it += grd_) {
;     const int b = it >> 7, r = it & 127, kvh = r >> 6, qblk = r & 63, t0 = qblk * 64, hq = kvh * 8 + wid;
;     const size_t tokb = (size_t)b * SEQ;
;     bf16x8 qf[2][4];
;     bf16_t* qrow0 = h + (tokb + t0 + c) * LDH + C_QA + hq * 64;
; #pragma unroll
;     for (int sub = 0; sub < 2; ++sub)
; #pragma unroll
;       for (int st = 0; st < 4; ++st) qf[sub][st] = *(const bf16x8*)(qrow0 + (size_t)sub * 32 * LDH + 16 * st + 8 * hh);
;     { const int key = tid >> 3, ch = tid & 7;
; #pragma unroll
;       for (int j = 0; j < 3; ++j) { int kp = t0 - 128 + 64 * j + key; kp = kp < 0 ? 0 : kp;
;         const bf16_t* src = h + (tokb + kp) * LDH + C_KA + kvh * 64 + ch * 8;
;         *(LAS u32x4*)(lds + j * 2 * TB + key * STR + ch * 16) = *(const u32x4*)src;
;         *(LAS u32x4*)(lds + j * 2 * TB + TB + key * VST + ch * 16) = *(const u32x4*)(src + (C_VA - C_KA)); } }
;     __syncthreads();
;     const float sink2 = p->sinks[l * 16 + hq] * LOG2E;
.LBB0_585:
	s_ashr_i32 s6, s16, 7
	s_and_b32 s23, s20, 0xfc0
	s_ashr_i32 s7, s6, 31
	s_bfe_u32 s1, s16, 0x10006
	s_lshl_b64 s[6:7], s[6:7], 12
	v_or_b32_e32 v151, s23, v133
	s_lshl_b32 s0, s1, 3
	v_or_b32_e32 v0, s6, v151
	s_add_i32 s0, s0, s19
	v_mad_u64_u32 v[0:1], s[8:9], v0, s91, v[130:131]
	v_mov_b32_e32 v2, 0x2280
	s_lshl_b32 s8, s0, 6
	v_mad_i32_i24 v1, s7, v2, v1
	s_ashr_i32 s9, s8, 31
	v_lshl_add_u64 v[136:137], s[8:9], 1, v[0:1]
	v_lshl_add_u64 v[0:1], v[136:137], 0, v[96:97]
	global_load_dwordx4 v[126:129], v[0:1], off
	global_load_dwordx4 v[122:125], v[0:1], off offset:32
	global_load_dwordx4 v[118:121], v[0:1], off offset:64
	global_load_dwordx4 v[114:117], v[0:1], off offset:96
	v_add_co_u32_e32 v0, vcc, s68, v0
	v_add_u32_e32 v6, s23, v139
	s_nop 0
	v_addc_co_u32_e32 v1, vcc, 0, v1, vcc
	global_load_dwordx4 v[110:113], v[0:1], off
	global_load_dwordx4 v[106:109], v[0:1], off offset:32
	global_load_dwordx4 v[102:105], v[0:1], off offset:64
	global_load_dwordx4 v[98:101], v[0:1], off offset:96
	v_max_i32_e32 v0, 0, v6
	v_mov_b32_e32 v1, v97
	v_lshl_add_u64 v[0:1], s[6:7], 0, v[0:1]
	v_mad_u64_u32 v[2:3], s[8:9], v0, s91, v[130:131]
	v_mad_i32_i24 v3, v1, s91, v3
	s_lshl_b32 s92, s1, 7
	v_lshl_add_u64 v[0:1], v[2:3], 0, s[92:93]
	v_mov_b32_e32 v135, v97
	v_lshl_add_u64 v[4:5], v[0:1], 0, v[134:135]
	global_load_dwordx4 v[8:11], v[4:5], off offset:2048
	global_load_dwordx4 v[12:15], v[4:5], off offset:2304
	s_add_i32 s0, s0, s18
	s_ashr_i32 s1, s0, 31
	s_lshl_b64 s[0:1], s[0:1], 2
	s_waitcnt lgkmcnt(0)
	s_add_u32 s0, s12, s0
	s_addc_u32 s1, s13, s1
	v_add_u32_e32 v172, 0xffffff80, v151
	v_max_i32_e32 v0, 0xffffffc0, v6
	v_add_u32_e32 v0, 64, v0
	v_mov_b32_e32 v1, v97
	v_lshl_add_u64 v[0:1], s[6:7], 0, v[0:1]
	v_mad_u64_u32 v[2:3], s[8:9], v0, s91, v[130:131]
	v_mad_i32_i24 v3, v1, s91, v3
	v_lshl_add_u64 v[0:1], v[2:3], 0, s[92:93]
	v_lshl_add_u64 v[4:5], v[0:1], 0, v[134:135]
	global_load_dwordx4 v[16:19], v[4:5], off offset:2048
	global_load_dwordx4 v[20:23], v[4:5], off offset:2304
	v_add_u32_e32 v0, s23, v138
	v_max_i32_e32 v0, 0, v0
	v_mov_b32_e32 v1, v97
	v_lshl_add_u64 v[0:1], s[6:7], 0, v[0:1]
	v_mad_u64_u32 v[2:3], s[6:7], v0, s91, v[130:131]
	v_mad_i32_i24 v3, v1, s91, v3
	v_lshl_add_u64 v[0:1], v[2:3], 0, s[92:93]
	v_lshl_add_u64 v[4:5], v[0:1], 0, v[134:135]
	global_load_dwordx4 v[24:27], v[4:5], off offset:2048
	global_load_dwordx4 v[28:31], v[4:5], off offset:2304
	global_load_dword v32, v97, s[0:1]
	v_add_u32_e32 v7, v142, v140
	s_waitcnt vmcnt(6)
	ds_write_b128 v7, v[8:11]
	v_add_u32_e32 v4, v143, v140
	s_waitcnt vmcnt(5)
	ds_write_b128 v4, v[12:15] offset:12288
	v_add_u32_e32 v6, v144, v140
	s_waitcnt vmcnt(4)
	ds_write_b128 v6, v[16:19] offset:24576
	v_add_u32_e32 v4, v145, v140
	s_waitcnt vmcnt(3)
	ds_write_b128 v4, v[20:23] offset:36864
	v_add_u32_e32 v6, v146, v140
	s_waitcnt vmcnt(2)
	ds_write_b128 v6, v[24:27] offset:49152
	s_waitcnt vmcnt(1)
	ds_write_b128 v149, v[28:31] offset:61440
	s_waitcnt lgkmcnt(0)
	s_barrier
	s_add_i32 s1, s23, 0xffffff81
	s_waitcnt vmcnt(0)
	v_mul_f32_e32 v135, 0x3fb8aa3b, v32
	v_mov_b32_e32 v0, 0x80
	v_sub_co_u32_e64 v0, s[6:7], s23, v0
	s_nop 0
	v_readfirstlane_b32 s0, v0
	s_or_b32 s24, s0, 63
	s_cmp_lt_u32 s24, s1
	s_cselect_b64 s[8:9], -1, 0
	s_or_b64 s[8:9], s[6:7], s[8:9]
	s_and_b64 vcc, exec, s[8:9]
	v_or_b32_e32 v153, v0, v132
	v_add_f32_e32 v152, 0x41000000, v135
	s_cbranch_vccnz .LBB0_588
	ds_read_b128 v[0:3], v150
	ds_read_b128 v[16:19], v150 offset:4608
	v_cmp_gt_i32_e32 vcc, v153, v172
	v_cmp_le_u32_e64 s[8:9], v153, v151
	s_and_b64 vcc, s[8:9], vcc
	s_waitcnt lgkmcnt(1)
	v_mfma_f32_32x32x16_bf16 v[0:15], v[0:3], v[126:129], 0
	s_waitcnt lgkmcnt(0)
	v_mfma_f32_32x32x16_bf16 v[16:31], v[16:19], v[126:129], 0
	ds_read_b128 v[32:35], v150 offset:32
	ds_read_b128 v[36:39], v150 offset:4640
	s_waitcnt lgkmcnt(1)
	v_mfma_f32_32x32x16_bf16 v[0:15], v[32:35], v[122:125], v[0:15]
	s_waitcnt lgkmcnt(0)
	v_mfma_f32_32x32x16_bf16 v[16:31], v[36:39], v[122:125], v[16:31]
	ds_read_b128 v[32:35], v150 offset:64
	ds_read_b128 v[36:39], v150 offset:4672
	s_waitcnt lgkmcnt(1)
	v_mfma_f32_32x32x16_bf16 v[0:15], v[32:35], v[118:121], v[0:15]
	ds_read_b128 v[32:35], v150 offset:96
	s_waitcnt lgkmcnt(1)
	v_mfma_f32_32x32x16_bf16 v[16:31], v[36:39], v[118:121], v[16:31]
	ds_read_b128 v[36:39], v150 offset:4704
	s_waitcnt lgkmcnt(1)
	v_mfma_f32_32x32x16_bf16 v[0:15], v[32:35], v[114:117], v[0:15]
	v_or_b32_e32 v32, 32, v153
	v_cmp_le_i32_e64 s[8:9], v32, v151
	v_cmp_gt_i32_e64 s[10:11], v32, v172
	s_and_b64 s[8:9], s[8:9], s[10:11]
	s_waitcnt lgkmcnt(0)
; template <int NQK, int NDV, int KSTR, int VSTR> ...
;     ...
;   if (domask) {
; #pragma unroll
;     for (int r = 0; r < 16; ++r) { const int kp = kpos0 + (r & 3) + 8 * (r >> 2) + 4 * h;
;       const bool v0 = (kp <= qpos) && (kp > qpos - window) && (kp >= 0);
;       const bool v1 = (kp + 32 <= qpos) && (kp + 32 > qpos - window) && (kp + 32 >= 0);
;       s0[r] = v0 ? s0[r] : -1e30f; s1[r] = v1 ? s1[r] : -1e30f; }
;   }
;   float mx = fmaxf(s0[0], s1[0]);
; #pragma unroll
;   for (int r = 1; r < 16; ++r) mx = fmaxf(mx, fmaxf(s0[r], s1[r]));
;   mx = fmaxf(mx, __shfl_xor(mx, 32));
;   if (__builtin_amdgcn_ballot_w64(mx > m + 8.0f) != 0ull) {
	v_mfma_f32_32x32x16_bf16 v[16:31], v[36:39], v[114:117], v[16:31]
	s_nop 5
	v_cndmask_b32_e32 v48, v247, v0, vcc
	v_cmp_ge_i32_e32 vcc, v153, v172
	v_or_b32_e32 v0, 33, v153
	v_cmp_gt_i32_e64 s[10:11], v0, v172
	s_nop 1
	v_cndmask_b32_e64 v49, v247, v16, s[8:9]
	v_cmp_lt_u32_e64 s[8:9], v153, v151
	s_and_b64 vcc, s[8:9], vcc
	v_cmp_le_i32_e64 s[8:9], v0, v151
	s_and_b64 s[8:9], s[8:9], s[10:11]
	v_or_b32_e32 v0, 2, v153
	v_cndmask_b32_e32 v51, v247, v1, vcc
	v_cndmask_b32_e64 v50, v247, v17, s[8:9]
	v_cmp_gt_i32_e32 vcc, v0, v172
	v_cmp_le_u32_e64 s[8:9], v0, v151
	v_or_b32_e32 v0, 34, v153
	s_and_b64 vcc, s[8:9], vcc
	v_cmp_le_i32_e64 s[8:9], v0, v151
	v_cmp_gt_i32_e64 s[10:11], v0, v172
	s_and_b64 s[8:9], s[8:9], s[10:11]
	v_or_b32_e32 v0, 3, v153
	v_cndmask_b32_e32 v45, v247, v2, vcc
	v_cndmask_b32_e64 v44, v247, v18, s[8:9]
	v_cmp_gt_i32_e32 vcc, v0, v172
	v_cmp_le_u32_e64 s[8:9], v0, v151
	v_or_b32_e32 v0, 35, v153
	s_and_b64 vcc, s[8:9], vcc
	v_cmp_le_i32_e64 s[8:9], v0, v151
	v_cmp_gt_i32_e64 s[10:11], v0, v172
	s_and_b64 s[8:9], s[8:9], s[10:11]
	v_or_b32_e32 v0, 8, v153
	v_cndmask_b32_e32 v47, v247, v3, vcc
	v_cndmask_b32_e64 v46, v247, v19, s[8:9]
	v_cmp_gt_i32_e32 vcc, v0, v172
	v_cmp_le_u32_e64 s[8:9], v0, v151
	v_or_b32_e32 v0, 40, v153
	s_and_b64 vcc, s[8:9], vcc
	v_cmp_le_i32_e64 s[8:9], v0, v151
	v_cmp_gt_i32_e64 s[10:11], v0, v172
	s_and_b64 s[8:9], s[8:9], s[10:11]
	v_or_b32_e32 v0, 9, v153
	v_cndmask_b32_e32 v41, v247, v4, vcc
	v_cndmask_b32_e64 v40, v247, v20, s[8:9]
	v_cmp_gt_i32_e32 vcc, v0, v172
	v_cmp_le_u32_e64 s[8:9], v0, v151
	v_or_b32_e32 v0, 41, v153
	s_and_b64 vcc, s[8:9], vcc
	v_cmp_le_i32_e64 s[8:9], v0, v151
	v_cmp_gt_i32_e64 s[10:11], v0, v172
	s_and_b64 s[8:9], s[8:9], s[10:11]
	v_or_b32_e32 v0, 10, v153
	v_cndmask_b32_e32 v43, v247, v5, vcc
	v_cndmask_b32_e64 v42, v247, v21, s[8:9]
	v_cmp_gt_i32_e32 vcc, v0, v172
	v_cmp_le_u32_e64 s[8:9], v0, v151
	v_or_b32_e32 v0, 42, v153
	s_and_b64 vcc, s[8:9], vcc
	v_cmp_le_i32_e64 s[8:9], v0, v151
	v_cmp_gt_i32_e64 s[10:11], v0, v172
	s_and_b64 s[8:9], s[8:9], s[10:11]
	v_or_b32_e32 v0, 11, v153
	v_cndmask_b32_e32 v37, v247, v6, vcc
	v_cndmask_b32_e64 v36, v247, v22, s[8:9]
	v_cmp_gt_i32_e32 vcc, v0, v172
	v_cmp_le_u32_e64 s[8:9], v0, v151
	v_or_b32_e32 v0, 43, v153
	s_and_b64 vcc, s[8:9], vcc
	v_cmp_le_i32_e64 s[8:9], v0, v151
	v_cmp_gt_i32_e64 s[10:11], v0, v172
	s_and_b64 s[8:9], s[8:9], s[10:11]
	v_or_b32_e32 v0, 16, v153
	v_cndmask_b32_e32 v39, v247, v7, vcc
	v_cndmask_b32_e64 v38, v247, v23, s[8:9]
	v_cmp_gt_i32_e32 vcc, v0, v172
	v_cmp_le_u32_e64 s[8:9], v0, v151
	v_or_b32_e32 v0, 48, v153
	s_and_b64 vcc, s[8:9], vcc
	v_cmp_le_i32_e64 s[8:9], v0, v151
	v_cmp_gt_i32_e64 s[10:11], v0, v172
	s_and_b64 s[8:9], s[8:9], s[10:11]
	v_or_b32_e32 v0, 17, v153
	v_cndmask_b32_e32 v33, v247, v8, vcc
	v_cndmask_b32_e64 v32, v247, v24, s[8:9]
	v_cmp_gt_i32_e32 vcc, v0, v172
	v_cmp_le_u32_e64 s[8:9], v0, v151
	v_or_b32_e32 v0, 49, v153
	s_and_b64 vcc, s[8:9], vcc
	v_cmp_le_i32_e64 s[8:9], v0, v151
	v_cmp_gt_i32_e64 s[10:11], v0, v172
	s_and_b64 s[8:9], s[8:9], s[10:11]
	v_or_b32_e32 v0, 18, v153
	v_cndmask_b32_e32 v35, v247, v9, vcc
	v_cndmask_b32_e64 v34, v247, v25, s[8:9]
	v_cmp_gt_i32_e32 vcc, v0, v172
	v_cmp_le_u32_e64 s[8:9], v0, v151
	v_or_b32_e32 v0, 50, v153
	s_and_b64 vcc, s[8:9], vcc
	v_cmp_le_i32_e64 s[8:9], v0, v151
	v_cmp_gt_i32_e64 s[10:11], v0, v172
	s_and_b64 s[8:9], s[8:9], s[10:11]
	v_or_b32_e32 v0, 19, v153
	v_cndmask_b32_e32 v9, v247, v10, vcc
	v_cndmask_b32_e64 v8, v247, v26, s[8:9]
	v_cmp_gt_i32_e32 vcc, v0, v172
	v_cmp_le_u32_e64 s[8:9], v0, v151
	v_or_b32_e32 v0, 51, v153
	s_and_b64 vcc, s[8:9], vcc
	v_cmp_le_i32_e64 s[8:9], v0, v151
	v_cmp_gt_i32_e64 s[10:11], v0, v172
	s_and_b64 s[8:9], s[8:9], s[10:11]
	v_or_b32_e32 v0, 24, v153
	v_cndmask_b32_e32 v11, v247, v11, vcc
	v_cndmask_b32_e64 v10, v247, v27, s[8:9]
	v_cmp_gt_i32_e32 vcc, v0, v172
	v_cmp_le_u32_e64 s[8:9], v0, v151
	v_or_b32_e32 v0, 56, v153
	s_and_b64 vcc, s[8:9], vcc
	v_cmp_le_i32_e64 s[8:9], v0, v151
	v_cmp_gt_i32_e64 s[10:11], v0, v172
	s_and_b64 s[8:9], s[8:9], s[10:11]
	v_or_b32_e32 v0, 25, v153
	v_cndmask_b32_e32 v5, v247, v12, vcc
	v_cndmask_b32_e64 v4, v247, v28, s[8:9]
	v_cmp_gt_i32_e32 vcc, v0, v172
	v_cmp_le_u32_e64 s[8:9], v0, v151
	v_or_b32_e32 v0, 57, v153
	s_and_b64 vcc, s[8:9], vcc
	v_cmp_le_i32_e64 s[8:9], v0, v151
	v_cmp_gt_i32_e64 s[10:11], v0, v172
	s_and_b64 s[8:9], s[8:9], s[10:11]
	v_or_b32_e32 v0, 26, v153
	v_cndmask_b32_e32 v7, v247, v13, vcc
	v_cndmask_b32_e64 v6, v247, v29, s[8:9]
	v_cmp_gt_i32_e32 vcc, v0, v172
	v_cmp_le_u32_e64 s[8:9], v0, v151
	v_or_b32_e32 v0, 58, v153
	s_and_b64 vcc, s[8:9], vcc
	v_cmp_le_i32_e64 s[8:9], v0, v151
	v_cmp_gt_i32_e64 s[10:11], v0, v172
	s_and_b64 s[8:9], s[8:9], s[10:11]
	v_or_b32_e32 v2, 27, v153
	v_cndmask_b32_e32 v1, v247, v14, vcc
	v_cndmask_b32_e64 v0, v247, v30, s[8:9]
	v_cmp_gt_i32_e32 vcc, v2, v172
	v_cmp_le_u32_e64 s[8:9], v2, v151
	v_max_f32_e32 v12, v50, v50
	v_max_f32_e32 v13, v51, v51
	s_and_b64 vcc, s[8:9], vcc
	v_max_f32_e32 v12, v13, v12
	v_max_f32_e32 v13, v44, v44
	v_max_f32_e32 v14, v45, v45
	v_cndmask_b32_e32 v3, v247, v15, vcc
	v_max_f32_e32 v13, v14, v13
	v_max_f32_e32 v14, v46, v46
	v_max_f32_e32 v15, v47, v47
	v_max3_f32 v12, v48, v49, v12
	v_max_f32_e32 v14, v15, v14
	v_max3_f32 v12, v12, v13, v14
	v_max_f32_e32 v13, v40, v40
	v_max_f32_e32 v14, v41, v41
	v_max_f32_e32 v13, v14, v13
	v_max_f32_e32 v14, v42, v42
	v_max_f32_e32 v15, v43, v43
	v_max_f32_e32 v14, v15, v14
	v_max3_f32 v12, v12, v13, v14
	v_max_f32_e32 v13, v36, v36
	v_max_f32_e32 v14, v37, v37
	v_max_f32_e32 v13, v14, v13
	v_max_f32_e32 v14, v38, v38
	v_max_f32_e32 v15, v39, v39
	v_max_f32_e32 v14, v15, v14
	v_max3_f32 v12, v12, v13, v14
	v_max_f32_e32 v13, v32, v32
	v_max_f32_e32 v14, v33, v33
	v_max_f32_e32 v13, v14, v13
	v_max_f32_e32 v14, v34, v34
	v_max_f32_e32 v15, v35, v35
	v_max_f32_e32 v14, v15, v14
	v_max3_f32 v12, v12, v13, v14
	v_max_f32_e32 v13, v8, v8
	v_max_f32_e32 v14, v9, v9
	v_max_f32_e32 v13, v14, v13
	v_max_f32_e32 v14, v10, v10
	v_max_f32_e32 v15, v11, v11
	v_max_f32_e32 v14, v15, v14
	v_or_b32_e32 v2, 59, v153
	v_max3_f32 v12, v12, v13, v14
	v_max_f32_e32 v13, v4, v4
	v_max_f32_e32 v14, v5, v5
	v_cmp_le_i32_e64 s[8:9], v2, v151
	v_cmp_gt_i32_e64 s[10:11], v2, v172
	v_max_f32_e32 v13, v14, v13
	v_max_f32_e32 v14, v6, v6
	v_max_f32_e32 v15, v7, v7
	s_and_b64 s[8:9], s[8:9], s[10:11]
	v_max_f32_e32 v14, v15, v14
	v_cndmask_b32_e64 v2, v247, v31, s[8:9]
	v_max3_f32 v12, v12, v13, v14
	v_max_f32_e32 v13, v0, v0
	v_max_f32_e32 v14, v1, v1
	v_max_f32_e32 v13, v14, v13
	v_max_f32_e32 v14, v2, v2
	v_max_f32_e32 v15, v3, v3
	v_max_f32_e32 v14, v15, v14
	v_max3_f32 v12, v12, v13, v14
	ds_bpermute_b32 v13, v141, v12
	s_waitcnt lgkmcnt(0)
	v_max_f32_e32 v13, v13, v13
	v_max_f32_e32 v12, v12, v13
	v_cmp_gt_f32_e32 vcc, v12, v152
	s_cbranch_vccz .LBB0_589
; __device__ __forceinline__ float fexp2(float x) { return __builtin_amdgcn_exp2f(x); }
; template <int NQK, int NDV, int KSTR, int VSTR> ...
;     ...
;   if (__builtin_amdgcn_ballot_w64(mx > m + 8.0f) != 0ull) {
;     const float mn = fmaxf(m, mx), alpha = fexp2(m - mn);
;     m = mn; l *= alpha;
; #pragma unroll
	v_max_f32_e32 v12, v12, v12
	v_max_f32_e32 v13, v135, v135
	v_max_f32_e32 v155, v13, v12
	v_sub_f32_e32 v12, v135, v155
	v_exp_f32_e32 v12, v12
	s_nop 0
	v_mul_f32_e32 v16, 0, v12
	s_branch .LBB0_590

; #define LAS __attribute__((address_space(3)))
;     ...
;     if (g != gprev) {
;       gprev = g;
;       const float* wg = p->sgu_w + ((size_t)l * 8 + g) * 128 * 128;
; #pragma unroll
;       for (int i = 0; i < 8; ++i) { const int idx = tid + 512 * i, t = idx >> 5, s4 = (idx & 31) * 4;
;         const f32x4 v = *(const f32x4*)(wg + t * 128 + s4);
;         u32x2 w; w.x = pk2(s4 <= t ? v[0] : 0.f, s4 + 1 <= t ? v[1] : 0.f); w.y = pk2(s4 + 2 <= t ? v[2] : 0.f, s4 + 3 <= t ? v[3] : 0.f);
;         *(LAS u32x2*)(Wl + t * STR + s4 * 2) = w; }
;     }
.LBB0_764:
	s_and_b32 s71, s78, 7
	s_cmp_eq_u32 s71, s1
	s_cbranch_scc1 .LBB0_763
	s_load_dwordx2 s[0:1], s[96:97], 0x58
	v_mov_b32_e32 v57, v97
	s_waitcnt lgkmcnt(0)
	s_add_u32 s0, s0, s76
	s_addc_u32 s1, s1, s77
	s_lshl_b32 s66, s71, 16
	s_add_u32 s0, s0, s66
	s_addc_u32 s1, s1, 0
	v_lshl_add_u64 v[0:1], s[0:1], 0, v[56:57]
	v_lshl_add_u64 v[2:3], v[38:39], 2, v[0:1]
	global_load_dwordx4 v[64:67], v[2:3], off
	v_lshl_add_u64 v[2:3], v[40:41], 2, v[0:1]
	global_load_dwordx4 v[68:71], v[2:3], off
	v_lshl_add_u64 v[2:3], v[42:43], 2, v[0:1]
	global_load_dwordx4 v[72:75], v[2:3], off
	v_lshl_add_u64 v[2:3], v[44:45], 2, v[0:1]
	global_load_dwordx4 v[76:79], v[2:3], off
	v_lshl_add_u64 v[2:3], v[46:47], 2, v[0:1]
	global_load_dwordx4 v[80:83], v[2:3], off
	v_lshl_add_u64 v[2:3], v[48:49], 2, v[0:1]
	global_load_dwordx4 v[84:87], v[2:3], off
	v_lshl_add_u64 v[2:3], v[50:51], 2, v[0:1]
	global_load_dwordx4 v[88:91], v[2:3], off
	v_lshl_add_u64 v[2:3], v[52:53], 2, v[0:1]
	global_load_dwordx4 v[92:95], v[2:3], off
	s_mov_b32 s1, s71
	s_waitcnt vmcnt(7)
	v_cndmask_b32_e64 v64, v64, 0, vcc
	v_cndmask_b32_e64 v65, 0, v65, s[2:3]
	v_cvt_pk_bf16_f32 v64, v64, v65
	v_cndmask_b32_e64 v65, v66, 0, s[4:5]
	v_cndmask_b32_e64 v66, v67, 0, s[6:7]
	v_cvt_pk_bf16_f32 v65, v65, v66
	ds_write_b64 v37, v[64:65]
	s_waitcnt vmcnt(6)
	v_cndmask_b32_e64 v68, v68, 0, s[8:9]
	v_cndmask_b32_e64 v69, 0, v69, s[10:11]
	v_cvt_pk_bf16_f32 v68, v68, v69
	v_cndmask_b32_e64 v69, v70, 0, s[12:13]
	v_cndmask_b32_e64 v70, v71, 0, s[14:15]
	v_cvt_pk_bf16_f32 v69, v69, v70
	ds_write_b64 v119, v[68:69]
	s_waitcnt vmcnt(5)
	v_cndmask_b32_e64 v72, v72, 0, s[16:17]
	v_cndmask_b32_e64 v73, 0, v73, s[18:19]
	v_cvt_pk_bf16_f32 v72, v72, v73
	v_cndmask_b32_e64 v73, v74, 0, s[20:21]
	v_cndmask_b32_e64 v74, v75, 0, s[22:23]
	v_cvt_pk_bf16_f32 v73, v73, v74
	ds_write_b64 v120, v[72:73]
	s_waitcnt vmcnt(4)
	v_cndmask_b32_e64 v76, v76, 0, s[24:25]
	v_cndmask_b32_e64 v77, 0, v77, s[26:27]
	v_cvt_pk_bf16_f32 v76, v76, v77
	v_cndmask_b32_e64 v77, v78, 0, s[28:29]
	v_cndmask_b32_e64 v78, v79, 0, s[30:31]
	v_cvt_pk_bf16_f32 v77, v77, v78
	ds_write_b64 v121, v[76:77]
	s_waitcnt vmcnt(3)
	v_cndmask_b32_e64 v80, v80, 0, s[34:35]
	v_cndmask_b32_e64 v81, 0, v81, s[36:37]
	v_cvt_pk_bf16_f32 v80, v80, v81
	v_cndmask_b32_e64 v81, v82, 0, s[38:39]
	v_cndmask_b32_e64 v82, v83, 0, s[40:41]
	v_cvt_pk_bf16_f32 v81, v81, v82
	ds_write_b64 v122, v[80:81]
	s_waitcnt vmcnt(2)
	v_cndmask_b32_e64 v84, v84, 0, s[42:43]
	v_cndmask_b32_e64 v85, 0, v85, s[44:45]
	v_cvt_pk_bf16_f32 v84, v84, v85
	v_cndmask_b32_e64 v85, v86, 0, s[46:47]
	v_cndmask_b32_e64 v86, v87, 0, s[48:49]
	v_cvt_pk_bf16_f32 v85, v85, v86
	ds_write_b64 v123, v[84:85]
	s_waitcnt vmcnt(1)
	v_cndmask_b32_e64 v88, v88, 0, s[50:51]
	v_cndmask_b32_e64 v89, 0, v89, s[52:53]
	v_cvt_pk_bf16_f32 v88, v88, v89
	v_cndmask_b32_e64 v89, v90, 0, s[54:55]
	v_cndmask_b32_e64 v90, v91, 0, s[56:57]
	v_cvt_pk_bf16_f32 v89, v89, v90
	ds_write_b64 v124, v[88:89]
	s_waitcnt vmcnt(0)
	v_cndmask_b32_e64 v92, v92, 0, s[58:59]
	v_cndmask_b32_e64 v93, 0, v93, s[60:61]
	v_cvt_pk_bf16_f32 v92, v92, v93
	v_cndmask_b32_e64 v93, v94, 0, s[62:63]
	v_cndmask_b32_e64 v94, v95, 0, s[64:65]
	v_cvt_pk_bf16_f32 v93, v93, v94
	ds_write_b64 v125, v[92:93]
	s_branch .LBB0_763

; #define LAS __attribute__((address_space(3)))
; __device__ __forceinline__ void mla_phase(KP p, LAS unsigned char* lds, int wv0) {
;     ...
;     for (int kt = 0; kt < ntiles; ++kt) {
;       LAS unsigned char* Kb = lds + (kt & 1) * KB; LAS unsigned char* Vb = lds + 2 * KB + (kt & 1) * VB;
;       *(LAS u32x4*)(Kb + kdst[0]) = kr0; *(LAS u32x4*)(Kb + kdst[1]) = kr1; *(LAS u32x4*)(Kb + kdst[2]) = kr2;
;       *(LAS u32x4*)(Vb + vdst[0]) = vr0; *(LAS u32x4*)(Vb + vdst[1]) = vr1;
;       __syncthreads();
;       if (kt + 1 < ntiles) {
;         ksrc[0] += k0rope ? kinc1 : kinc0; ksrc[1] += k1rope ? kinc1 : kinc0; ksrc[2] += k2rope ? kinc1 : kinc0; vsrc[0] += kinc0; vsrc[1] += kinc0;
;         kr0 = *(const u32x4*)(wsb + ksrc[0]); kr1 = *(const u32x4*)(wsb + ksrc[1]); kr2 = *(const u32x4*)(wsb + ksrc[2]); vr0 = *(const u32x4*)(wsb + vsrc[0]); vr1 = *(const u32x4*)(wsb + vsrc[1]);
;       }
;       const int k0 = kt * 64;
;       if (k0 <= q0 + 31) attn_tile<12, 4, KSTR, VSTR>(qf, o, m, l, Kb, Vb, lane, q0 + c, k0, 1 << 30, k0 + 63 > q0);
.Lmla_entry:
	s_cmp_ge_u32 s53, 4
	s_cbranch_scc0 .Lmla_noprio
	s_setprio 1

; #define LAS __attribute__((address_space(3)))
; __device__ __forceinline__ float frcp(float x) { return __builtin_amdgcn_rcpf(x); }
; __device__ __forceinline__ void mla_phase(KP p, LAS unsigned char* lds, int wv0) {
;     ...
;     for (int kt = 0; kt < ntiles; ++kt) {
;       LAS unsigned char* Kb = lds + (kt & 1) * KB; LAS unsigned char* Vb = lds + 2 * KB + (kt & 1) * VB;
;       *(LAS u32x4*)(Kb + kdst[0]) = kr0; *(LAS u32x4*)(Kb + kdst[1]) = kr1; *(LAS u32x4*)(Kb + kdst[2]) = kr2;
;       *(LAS u32x4*)(Vb + vdst[0]) = vr0; *(LAS u32x4*)(Vb + vdst[1]) = vr1;
;       __syncthreads();
;       if (kt + 1 < ntiles) {
;         ksrc[0] += k0rope ? kinc1 : kinc0; ksrc[1] += k1rope ? kinc1 : kinc0; ksrc[2] += k2rope ? kinc1 : kinc0; vsrc[0] += kinc0; vsrc[1] += kinc0;
;         kr0 = *(const u32x4*)(wsb + ksrc[0]); kr1 = *(const u32x4*)(wsb + ksrc[1]); kr2 = *(const u32x4*)(wsb + ksrc[2]); vr0 = *(const u32x4*)(wsb + vsrc[0]); vr1 = *(const u32x4*)(wsb + vsrc[1]);
;       }
;       const int k0 = kt * 64;
;       if (k0 <= q0 + 31) attn_tile<12, 4, KSTR, VSTR>(qf, o, m, l, Kb, Vb, lane, q0 + c, k0, 1 << 30, k0 + 63 > q0);
;     }
;     const float inv = frcp(l + __shfl_xor(l, 32));
.Lmla_s4_done:
	s_mov_b32 s35, s34
	s_mov_b32 s34, s36
	s_add_u32 s36, s36, 0x5000
	s_cmp_eq_u32 s36, 0x1b800
	s_cselect_b32 s36, 0xc800, s36
	s_xor_b32 s32, s32, 0x6400
	s_add_u32 s28, s28, 1
	s_cmp_le_u32 s28, s29
	s_cbranch_scc1 .Lmla_iter
	s_setprio 0
	s_branch .LBB0_821
